# prep weight transposes rewritten by hand: 4 tiles of loads in flight, double-buffered LDS, 1 barrier per tile
# speedup vs baseline: 1.0549x; 1.0084x over previous
.Ltr_go:
	s_add_u32 s74, s34, 0xfffffe50
	s_addc_u32 s75, s35, -1
	s_cmpk_eq_u32 s98, 0xc0
	s_cselect_b32 s73, 1, 3
	v_and_b32_e32 v20, 63, v235
	v_lshrrev_b32_e32 v21, 6, v235
	v_lshrrev_b32_e32 v112, 2, v235
	v_and_b32_e32 v113, 3, v235
	v_mul_u32_u24_e32 v1, 0x41, v21
	v_add_u32_e32 v1, v1, v20
	v_lshl_add_u32 v22, v1, 2, s72
	v_add_u32_e32 v23, 0x4200, v22
	v_mul_u32_u24_e32 v1, 0x1040, v113
	v_lshl_add_u32 v1, v112, 2, v1
	v_add_u32_e32 v24, s72, v1
	v_add_u32_e32 v25, 0x400, v24
	v_add_u32_e32 v26, 0x800, v24
	v_add_u32_e32 v27, 0xc00, v24
	v_add_u32_e32 v28, 0x4200, v24
	v_add_u32_e32 v29, 0x4200, v25
	v_add_u32_e32 v30, 0x4200, v26
	v_add_u32_e32 v31, 0x4200, v27
	v_lshlrev_b32_e32 v113, 5, v113
	s_cmpk_ge_u32 s40, 0x700
	s_cselect_b32 s0, 1, 0
	s_mul_i32 s1, s0, 0x700
	s_sub_u32 s1, s40, s1
	s_cmpk_ge_u32 s1, 0x4c0
	s_cbranch_scc1 .Ltp_c1_1
	s_movk_i32 s41, 0x50
	s_movk_i32 s42, 0xe8
	s_movk_i32 s43, 0x1210
	s_mov_b32 s44, 4
	s_movk_i32 s45, 0x880
	s_mov_b32 s46, 0x1210000
	s_mov_b32 s47, 0xa18000
	s_branch .Ltp_cj_1
.Ltp_c1_1:
	s_cmpk_ge_u32 s1, 0x500
	s_cbranch_scc1 .Ltp_c2_1
	s_sub_u32 s1, s1, 0x4c0
	s_movk_i32 s41, 0xb0
	s_movk_i32 s42, 0xf0
	s_movk_i32 s43, 0x200
	s_mov_b32 s44, 3
	s_movk_i32 s45, 0x400
	s_mov_b32 s46, 0x100000
	s_mov_b32 s47, 0x80000
	s_branch .Ltp_cj_1
.Ltp_c2_1:
	s_cmpk_ge_u32 s1, 0x580
	s_cbranch_scc1 .Ltp_c3_1
	s_sub_u32 s1, s1, 0x500
	s_movk_i32 s41, 0xc0
	s_movk_i32 s42, 0xf8
	s_movk_i32 s43, 0x400
	s_mov_b32 s44, 3
	s_movk_i32 s45, 0x400
	s_mov_b32 s46, 0x200000
	s_mov_b32 s47, 0x100000
	s_branch .Ltp_cj_1
.Ltp_c3_1:
	s_cmpk_ge_u32 s1, 0x600
	s_cbranch_scc1 .Ltp_c4_1
	s_sub_u32 s1, s1, 0x580
	s_movk_i32 s41, 0xc8
	s_movk_i32 s42, 0x100
	s_movk_i32 s43, 0x400
	s_mov_b32 s44, 3
	s_movk_i32 s45, 0x400
	s_mov_b32 s46, 0x200000
	s_mov_b32 s47, 0x100000
	s_branch .Ltp_cj_1
.Ltp_c4_1:
	s_sub_u32 s1, s1, 0x600
	s_movk_i32 s41, 0xd0
	s_movk_i32 s42, 0x108
	s_movk_i32 s43, 0x400
	s_mov_b32 s44, 4
	s_movk_i32 s45, 0x800
	s_mov_b32 s46, 0x400000
	s_mov_b32 s47, 0x200000
.Ltp_cj_1:
	s_load_dwordx2 s[48:49], s[74:75], s41
	s_load_dwordx2 s[50:51], s[74:75], s42
	s_lshr_b32 s52, s1, s44
	s_lshl_b32 s53, s52, s44
	s_sub_u32 s53, s1, s53
	s_lshl_b32 s52, s52, 6
	s_lshl_b32 s53, s53, 6
	s_sub_i32 s76, s43, s52
	s_mov_b32 s77, s45
	s_mul_i32 s54, s0, s46
	s_mul_i32 s55, s53, s43
	s_lshl_b32 s55, s55, 2
	s_add_u32 s54, s54, s55
	s_mul_i32 s55, s0, s47
	s_mul_i32 s41, s52, s45
	s_add_u32 s55, s55, s41
	s_lshl_b32 s41, s53, 1
	s_add_u32 s55, s55, s41
	s_add_i32 s41, s43, -1
	v_add_u32_e32 v3, s52, v20
	v_min_u32_e32 v3, s41, v3
	s_lshl_b32 s42, s43, 2
	v_mul_u32_u24_e32 v1, s42, v21
	v_lshl_add_u32 v1, v3, 2, v1
	s_lshl_b32 s42, s43, 4
	s_add_i32 s40, s40, s98
	s_waitcnt lgkmcnt(0)
	s_add_u32 s4, s48, s54
	s_addc_u32 s5, s49, 0
	s_add_u32 s78, s50, s55
	s_addc_u32 s79, s51, 0
	s_add_u32 s6, s4, s42
	s_addc_u32 s7, s5, 0
	s_add_u32 s8, s6, s42
	s_addc_u32 s9, s7, 0
	s_add_u32 s10, s8, s42
	s_addc_u32 s11, s9, 0
	s_add_u32 s12, s10, s42
	s_addc_u32 s13, s11, 0
	s_add_u32 s14, s12, s42
	s_addc_u32 s15, s13, 0
	s_add_u32 s16, s14, s42
	s_addc_u32 s17, s15, 0
	s_add_u32 s18, s16, s42
	s_addc_u32 s19, s17, 0
	s_add_u32 s20, s18, s42
	s_addc_u32 s21, s19, 0
	s_add_u32 s22, s20, s42
	s_addc_u32 s23, s21, 0
	s_add_u32 s24, s22, s42
	s_addc_u32 s25, s23, 0
	s_add_u32 s26, s24, s42
	s_addc_u32 s27, s25, 0
	s_add_u32 s28, s26, s42
	s_addc_u32 s29, s27, 0
	s_add_u32 s30, s28, s42
	s_addc_u32 s31, s29, 0
	s_add_u32 s36, s30, s42
	s_addc_u32 s37, s31, 0
	s_add_u32 s38, s36, s42
	s_addc_u32 s39, s37, 0
	s_nop 4
	global_load_dword v32, v1, s[4:5] nt
	global_load_dword v33, v1, s[6:7] nt
	global_load_dword v34, v1, s[8:9] nt
	global_load_dword v35, v1, s[10:11] nt
	global_load_dword v36, v1, s[12:13] nt
	global_load_dword v37, v1, s[14:15] nt
	global_load_dword v38, v1, s[16:17] nt
	global_load_dword v39, v1, s[18:19] nt
	global_load_dword v40, v1, s[20:21] nt
	global_load_dword v41, v1, s[22:23] nt
	global_load_dword v42, v1, s[24:25] nt
	global_load_dword v43, v1, s[26:27] nt
	global_load_dword v44, v1, s[28:29] nt
	global_load_dword v45, v1, s[30:31] nt
	global_load_dword v46, v1, s[36:37] nt
	global_load_dword v47, v1, s[38:39] nt
	s_cmpk_ge_u32 s40, 0x700
	s_cselect_b32 s0, 1, 0
	s_mul_i32 s1, s0, 0x700
	s_sub_u32 s1, s40, s1
	s_cmpk_ge_u32 s1, 0x4c0
	s_cbranch_scc1 .Ltp_c1_2
	s_movk_i32 s41, 0x50
	s_movk_i32 s42, 0xe8
	s_movk_i32 s43, 0x1210
	s_mov_b32 s44, 4
	s_movk_i32 s45, 0x880
	s_mov_b32 s46, 0x1210000
	s_mov_b32 s47, 0xa18000
	s_branch .Ltp_cj_2

.Ltp_cj_2:
	s_load_dwordx2 s[48:49], s[74:75], s41
	s_load_dwordx2 s[50:51], s[74:75], s42
	s_lshr_b32 s52, s1, s44
	s_lshl_b32 s53, s52, s44
	s_sub_u32 s53, s1, s53
	s_lshl_b32 s52, s52, 6
	s_lshl_b32 s53, s53, 6
	s_sub_i32 s80, s43, s52
	s_mov_b32 s81, s45
	s_mul_i32 s54, s0, s46
	s_mul_i32 s55, s53, s43
	s_lshl_b32 s55, s55, 2
	s_add_u32 s54, s54, s55
	s_mul_i32 s55, s0, s47
	s_mul_i32 s41, s52, s45
	s_add_u32 s55, s55, s41
	s_lshl_b32 s41, s53, 1
	s_add_u32 s55, s55, s41
	s_add_i32 s41, s43, -1
	v_add_u32_e32 v3, s52, v20
	v_min_u32_e32 v3, s41, v3
	s_lshl_b32 s42, s43, 2
	v_mul_u32_u24_e32 v1, s42, v21
	v_lshl_add_u32 v1, v3, 2, v1
	s_lshl_b32 s42, s43, 4
	s_add_i32 s40, s40, s98
	s_waitcnt lgkmcnt(0)
	s_add_u32 s4, s48, s54
	s_addc_u32 s5, s49, 0
	s_add_u32 s82, s50, s55
	s_addc_u32 s83, s51, 0
	s_add_u32 s6, s4, s42
	s_addc_u32 s7, s5, 0
	s_add_u32 s8, s6, s42
	s_addc_u32 s9, s7, 0
	s_add_u32 s10, s8, s42
	s_addc_u32 s11, s9, 0
	s_add_u32 s12, s10, s42
	s_addc_u32 s13, s11, 0
	s_add_u32 s14, s12, s42
	s_addc_u32 s15, s13, 0
	s_add_u32 s16, s14, s42
	s_addc_u32 s17, s15, 0
	s_add_u32 s18, s16, s42
	s_addc_u32 s19, s17, 0
	s_add_u32 s20, s18, s42
	s_addc_u32 s21, s19, 0
	s_add_u32 s22, s20, s42
	s_addc_u32 s23, s21, 0
	s_add_u32 s24, s22, s42
	s_addc_u32 s25, s23, 0
	s_add_u32 s26, s24, s42
	s_addc_u32 s27, s25, 0
	s_add_u32 s28, s26, s42
	s_addc_u32 s29, s27, 0
	s_add_u32 s30, s28, s42
	s_addc_u32 s31, s29, 0
	s_add_u32 s36, s30, s42
	s_addc_u32 s37, s31, 0
	s_add_u32 s38, s36, s42
	s_addc_u32 s39, s37, 0
	s_nop 4
	global_load_dword v48, v1, s[4:5] nt
	global_load_dword v49, v1, s[6:7] nt
	global_load_dword v50, v1, s[8:9] nt
	global_load_dword v51, v1, s[10:11] nt
	global_load_dword v52, v1, s[12:13] nt
	global_load_dword v53, v1, s[14:15] nt
	global_load_dword v54, v1, s[16:17] nt
	global_load_dword v55, v1, s[18:19] nt
	global_load_dword v56, v1, s[20:21] nt
	global_load_dword v57, v1, s[22:23] nt
	global_load_dword v58, v1, s[24:25] nt
	global_load_dword v59, v1, s[26:27] nt
	global_load_dword v60, v1, s[28:29] nt
	global_load_dword v61, v1, s[30:31] nt
	global_load_dword v62, v1, s[36:37] nt
	global_load_dword v63, v1, s[38:39] nt
	s_cmpk_ge_u32 s40, 0x700
	s_cselect_b32 s0, 1, 0
	s_mul_i32 s1, s0, 0x700
	s_sub_u32 s1, s40, s1
	s_cmpk_ge_u32 s1, 0x4c0
	s_cbranch_scc1 .Ltp_c1_3
	s_movk_i32 s41, 0x50
	s_movk_i32 s42, 0xe8
	s_movk_i32 s43, 0x1210
	s_mov_b32 s44, 4
	s_movk_i32 s45, 0x880
	s_mov_b32 s46, 0x1210000
	s_mov_b32 s47, 0xa18000
	s_branch .Ltp_cj_3

.Ltp_cj_3:
	s_load_dwordx2 s[48:49], s[74:75], s41
	s_load_dwordx2 s[50:51], s[74:75], s42
	s_lshr_b32 s52, s1, s44
	s_lshl_b32 s53, s52, s44
	s_sub_u32 s53, s1, s53
	s_lshl_b32 s52, s52, 6
	s_lshl_b32 s53, s53, 6
	s_sub_i32 s84, s43, s52
	s_mov_b32 s85, s45
	s_mul_i32 s54, s0, s46
	s_mul_i32 s55, s53, s43
	s_lshl_b32 s55, s55, 2
	s_add_u32 s54, s54, s55
	s_mul_i32 s55, s0, s47
	s_mul_i32 s41, s52, s45
	s_add_u32 s55, s55, s41
	s_lshl_b32 s41, s53, 1
	s_add_u32 s55, s55, s41
	s_add_i32 s41, s43, -1
	v_add_u32_e32 v3, s52, v20
	v_min_u32_e32 v3, s41, v3
	s_lshl_b32 s42, s43, 2
	v_mul_u32_u24_e32 v1, s42, v21
	v_lshl_add_u32 v1, v3, 2, v1
	s_lshl_b32 s42, s43, 4
	s_add_i32 s40, s40, s98
	s_waitcnt lgkmcnt(0)
	s_add_u32 s4, s48, s54
	s_addc_u32 s5, s49, 0
	s_add_u32 s86, s50, s55
	s_addc_u32 s87, s51, 0
	s_add_u32 s6, s4, s42
	s_addc_u32 s7, s5, 0
	s_add_u32 s8, s6, s42
	s_addc_u32 s9, s7, 0
	s_add_u32 s10, s8, s42
	s_addc_u32 s11, s9, 0
	s_add_u32 s12, s10, s42
	s_addc_u32 s13, s11, 0
	s_add_u32 s14, s12, s42
	s_addc_u32 s15, s13, 0
	s_add_u32 s16, s14, s42
	s_addc_u32 s17, s15, 0
	s_add_u32 s18, s16, s42
	s_addc_u32 s19, s17, 0
	s_add_u32 s20, s18, s42
	s_addc_u32 s21, s19, 0
	s_add_u32 s22, s20, s42
	s_addc_u32 s23, s21, 0
	s_add_u32 s24, s22, s42
	s_addc_u32 s25, s23, 0
	s_add_u32 s26, s24, s42
	s_addc_u32 s27, s25, 0
	s_add_u32 s28, s26, s42
	s_addc_u32 s29, s27, 0
	s_add_u32 s30, s28, s42
	s_addc_u32 s31, s29, 0
	s_add_u32 s36, s30, s42
	s_addc_u32 s37, s31, 0
	s_add_u32 s38, s36, s42
	s_addc_u32 s39, s37, 0
	s_nop 4
	global_load_dword v64, v1, s[4:5] nt
	global_load_dword v65, v1, s[6:7] nt
	global_load_dword v66, v1, s[8:9] nt
	global_load_dword v67, v1, s[10:11] nt
	global_load_dword v68, v1, s[12:13] nt
	global_load_dword v69, v1, s[14:15] nt
	global_load_dword v70, v1, s[16:17] nt
	global_load_dword v71, v1, s[18:19] nt
	global_load_dword v72, v1, s[20:21] nt
	global_load_dword v73, v1, s[22:23] nt
	global_load_dword v74, v1, s[24:25] nt
	global_load_dword v75, v1, s[26:27] nt
	global_load_dword v76, v1, s[28:29] nt
	global_load_dword v77, v1, s[30:31] nt
	global_load_dword v78, v1, s[36:37] nt
	global_load_dword v79, v1, s[38:39] nt
	s_cmpk_ge_u32 s40, 0x700
	s_cselect_b32 s0, 1, 0
	s_mul_i32 s1, s0, 0x700
	s_sub_u32 s1, s40, s1
	s_cmpk_ge_u32 s1, 0x4c0
	s_cbranch_scc1 .Ltp_c1_4
	s_movk_i32 s41, 0x50
	s_movk_i32 s42, 0xe8
	s_movk_i32 s43, 0x1210
	s_mov_b32 s44, 4
	s_movk_i32 s45, 0x880
	s_mov_b32 s46, 0x1210000
	s_mov_b32 s47, 0xa18000
	s_branch .Ltp_cj_4

.Ltp_cj_4:
	s_load_dwordx2 s[48:49], s[74:75], s41
	s_load_dwordx2 s[50:51], s[74:75], s42
	s_lshr_b32 s52, s1, s44
	s_lshl_b32 s53, s52, s44
	s_sub_u32 s53, s1, s53
	s_lshl_b32 s52, s52, 6
	s_lshl_b32 s53, s53, 6
	s_sub_i32 s88, s43, s52
	s_mov_b32 s89, s45
	s_mul_i32 s54, s0, s46
	s_mul_i32 s55, s53, s43
	s_lshl_b32 s55, s55, 2
	s_add_u32 s54, s54, s55
	s_mul_i32 s55, s0, s47
	s_mul_i32 s41, s52, s45
	s_add_u32 s55, s55, s41
	s_lshl_b32 s41, s53, 1
	s_add_u32 s55, s55, s41
	s_add_i32 s41, s43, -1
	v_add_u32_e32 v3, s52, v20
	v_min_u32_e32 v3, s41, v3
	s_lshl_b32 s42, s43, 2
	v_mul_u32_u24_e32 v1, s42, v21
	v_lshl_add_u32 v1, v3, 2, v1
	s_lshl_b32 s42, s43, 4
	s_add_i32 s40, s40, s98
	s_waitcnt lgkmcnt(0)
	s_add_u32 s4, s48, s54
	s_addc_u32 s5, s49, 0
	s_add_u32 s90, s50, s55
	s_addc_u32 s91, s51, 0
	s_add_u32 s6, s4, s42
	s_addc_u32 s7, s5, 0
	s_add_u32 s8, s6, s42
	s_addc_u32 s9, s7, 0
	s_add_u32 s10, s8, s42
	s_addc_u32 s11, s9, 0
	s_add_u32 s12, s10, s42
	s_addc_u32 s13, s11, 0
	s_add_u32 s14, s12, s42
	s_addc_u32 s15, s13, 0
	s_add_u32 s16, s14, s42
	s_addc_u32 s17, s15, 0
	s_add_u32 s18, s16, s42
	s_addc_u32 s19, s17, 0
	s_add_u32 s20, s18, s42
	s_addc_u32 s21, s19, 0
	s_add_u32 s22, s20, s42
	s_addc_u32 s23, s21, 0
	s_add_u32 s24, s22, s42
	s_addc_u32 s25, s23, 0
	s_add_u32 s26, s24, s42
	s_addc_u32 s27, s25, 0
	s_add_u32 s28, s26, s42
	s_addc_u32 s29, s27, 0
	s_add_u32 s30, s28, s42
	s_addc_u32 s31, s29, 0
	s_add_u32 s36, s30, s42
	s_addc_u32 s37, s31, 0
	s_add_u32 s38, s36, s42
	s_addc_u32 s39, s37, 0
	s_nop 4
	global_load_dword v96, v1, s[4:5] nt
	global_load_dword v97, v1, s[6:7] nt
	global_load_dword v98, v1, s[8:9] nt
	global_load_dword v99, v1, s[10:11] nt
	global_load_dword v100, v1, s[12:13] nt
	global_load_dword v101, v1, s[14:15] nt
	global_load_dword v102, v1, s[16:17] nt
	global_load_dword v103, v1, s[18:19] nt
	global_load_dword v104, v1, s[20:21] nt
	global_load_dword v105, v1, s[22:23] nt
	global_load_dword v106, v1, s[24:25] nt
	global_load_dword v107, v1, s[26:27] nt
	global_load_dword v108, v1, s[28:29] nt
	global_load_dword v109, v1, s[30:31] nt
	global_load_dword v110, v1, s[36:37] nt
	global_load_dword v111, v1, s[38:39] nt
	s_waitcnt vmcnt(48)
	s_cmpk_ge_i32 s76, 0x40
	s_cbranch_scc1 .Ltp_nz_5
	v_cmp_gt_i32_e32 vcc, s76, v20
	v_cndmask_b32_e32 v32, 0, v32, vcc
	v_cndmask_b32_e32 v33, 0, v33, vcc
	v_cndmask_b32_e32 v34, 0, v34, vcc
	v_cndmask_b32_e32 v35, 0, v35, vcc
	v_cndmask_b32_e32 v36, 0, v36, vcc
	v_cndmask_b32_e32 v37, 0, v37, vcc
	v_cndmask_b32_e32 v38, 0, v38, vcc
	v_cndmask_b32_e32 v39, 0, v39, vcc
	v_cndmask_b32_e32 v40, 0, v40, vcc
	v_cndmask_b32_e32 v41, 0, v41, vcc
	v_cndmask_b32_e32 v42, 0, v42, vcc
	v_cndmask_b32_e32 v43, 0, v43, vcc
	v_cndmask_b32_e32 v44, 0, v44, vcc
	v_cndmask_b32_e32 v45, 0, v45, vcc
	v_cndmask_b32_e32 v46, 0, v46, vcc
	v_cndmask_b32_e32 v47, 0, v47, vcc
.Ltp_nz_5:
	ds_write_b32 v22, v32
	ds_write_b32 v22, v33 offset:1040
	ds_write_b32 v22, v34 offset:2080
	ds_write_b32 v22, v35 offset:3120
	ds_write_b32 v22, v36 offset:4160
	ds_write_b32 v22, v37 offset:5200
	ds_write_b32 v22, v38 offset:6240
	ds_write_b32 v22, v39 offset:7280
	ds_write_b32 v22, v40 offset:8320
	ds_write_b32 v22, v41 offset:9360
	ds_write_b32 v22, v42 offset:10400
	ds_write_b32 v22, v43 offset:11440
	ds_write_b32 v22, v44 offset:12480
	ds_write_b32 v22, v45 offset:13520
	ds_write_b32 v22, v46 offset:14560
	ds_write_b32 v22, v47 offset:15600
	v_mov_b32_e32 v3, s77
	v_mad_u32_u24 v2, v112, v3, v113
	s_mov_b64 s[94:95], s[78:79]
	s_cmpk_ge_u32 s40, 0x700
	s_cselect_b32 s0, 1, 0
	s_mul_i32 s1, s0, 0x700
	s_sub_u32 s1, s40, s1
	s_cmpk_ge_u32 s1, 0x4c0
	s_cbranch_scc1 .Ltp_c1_6
	s_movk_i32 s41, 0x50
	s_movk_i32 s42, 0xe8
	s_movk_i32 s43, 0x1210
	s_mov_b32 s44, 4
	s_movk_i32 s45, 0x880
	s_mov_b32 s46, 0x1210000
	s_mov_b32 s47, 0xa18000
	s_branch .Ltp_cj_6

.Ltp_cj_6:
	s_load_dwordx2 s[48:49], s[74:75], s41
	s_load_dwordx2 s[50:51], s[74:75], s42
	s_lshr_b32 s52, s1, s44
	s_lshl_b32 s53, s52, s44
	s_sub_u32 s53, s1, s53
	s_lshl_b32 s52, s52, 6
	s_lshl_b32 s53, s53, 6
	s_sub_i32 s76, s43, s52
	s_mov_b32 s77, s45
	s_mul_i32 s54, s0, s46
	s_mul_i32 s55, s53, s43
	s_lshl_b32 s55, s55, 2
	s_add_u32 s54, s54, s55
	s_mul_i32 s55, s0, s47
	s_mul_i32 s41, s52, s45
	s_add_u32 s55, s55, s41
	s_lshl_b32 s41, s53, 1
	s_add_u32 s55, s55, s41
	s_add_i32 s41, s43, -1
	v_add_u32_e32 v3, s52, v20
	v_min_u32_e32 v3, s41, v3
	s_lshl_b32 s42, s43, 2
	v_mul_u32_u24_e32 v1, s42, v21
	v_lshl_add_u32 v1, v3, 2, v1
	s_lshl_b32 s42, s43, 4
	s_add_i32 s40, s40, s98
	s_waitcnt lgkmcnt(0)
	s_add_u32 s4, s48, s54
	s_addc_u32 s5, s49, 0
	s_add_u32 s78, s50, s55
	s_addc_u32 s79, s51, 0
	s_add_u32 s6, s4, s42
	s_addc_u32 s7, s5, 0
	s_add_u32 s8, s6, s42
	s_addc_u32 s9, s7, 0
	s_add_u32 s10, s8, s42
	s_addc_u32 s11, s9, 0
	s_add_u32 s12, s10, s42
	s_addc_u32 s13, s11, 0
	s_add_u32 s14, s12, s42
	s_addc_u32 s15, s13, 0
	s_add_u32 s16, s14, s42
	s_addc_u32 s17, s15, 0
	s_add_u32 s18, s16, s42
	s_addc_u32 s19, s17, 0
	s_add_u32 s20, s18, s42
	s_addc_u32 s21, s19, 0
	s_add_u32 s22, s20, s42
	s_addc_u32 s23, s21, 0
	s_add_u32 s24, s22, s42
	s_addc_u32 s25, s23, 0
	s_add_u32 s26, s24, s42
	s_addc_u32 s27, s25, 0
	s_add_u32 s28, s26, s42
	s_addc_u32 s29, s27, 0
	s_add_u32 s30, s28, s42
	s_addc_u32 s31, s29, 0
	s_add_u32 s36, s30, s42
	s_addc_u32 s37, s31, 0
	s_add_u32 s38, s36, s42
	s_addc_u32 s39, s37, 0
	s_nop 4
	global_load_dword v32, v1, s[4:5] nt
	global_load_dword v33, v1, s[6:7] nt
	global_load_dword v34, v1, s[8:9] nt
	global_load_dword v35, v1, s[10:11] nt
	global_load_dword v36, v1, s[12:13] nt
	global_load_dword v37, v1, s[14:15] nt
	global_load_dword v38, v1, s[16:17] nt
	global_load_dword v39, v1, s[18:19] nt
	global_load_dword v40, v1, s[20:21] nt
	global_load_dword v41, v1, s[22:23] nt
	global_load_dword v42, v1, s[24:25] nt
	global_load_dword v43, v1, s[26:27] nt
	global_load_dword v44, v1, s[28:29] nt
	global_load_dword v45, v1, s[30:31] nt
	global_load_dword v46, v1, s[36:37] nt
	global_load_dword v47, v1, s[38:39] nt
	s_waitcnt lgkmcnt(0)
	s_barrier
	ds_read2_b32 v[4:5], v24 offset1:65
	ds_read2_b32 v[6:7], v24 offset0:130 offset1:195
	ds_read2_b32 v[8:9], v25 offset0:4 offset1:69
	ds_read2_b32 v[10:11], v25 offset0:134 offset1:199
	ds_read2_b32 v[12:13], v26 offset0:8 offset1:73
	ds_read2_b32 v[14:15], v26 offset0:138 offset1:203
	ds_read2_b32 v[16:17], v27 offset0:12 offset1:77
	ds_read2_b32 v[18:19], v27 offset0:142 offset1:207
	s_waitcnt lgkmcnt(4)
	v_cvt_pk_bf16_f32 v4, v4, v5
	v_cvt_pk_bf16_f32 v5, v6, v7
	v_cvt_pk_bf16_f32 v6, v8, v9
	v_cvt_pk_bf16_f32 v7, v10, v11
	global_store_dwordx4 v2, v[4:7], s[94:95]
	s_waitcnt lgkmcnt(0)
	v_cvt_pk_bf16_f32 v8, v12, v13
	v_cvt_pk_bf16_f32 v9, v14, v15
	v_cvt_pk_bf16_f32 v10, v16, v17
	v_cvt_pk_bf16_f32 v11, v18, v19
	global_store_dwordx4 v2, v[8:11], s[94:95] offset:16
	s_waitcnt vmcnt(50)
	s_cmpk_ge_i32 s80, 0x40
	s_cbranch_scc1 .Ltp_nz_7
	v_cmp_gt_i32_e32 vcc, s80, v20
	v_cndmask_b32_e32 v48, 0, v48, vcc
	v_cndmask_b32_e32 v49, 0, v49, vcc
	v_cndmask_b32_e32 v50, 0, v50, vcc
	v_cndmask_b32_e32 v51, 0, v51, vcc
	v_cndmask_b32_e32 v52, 0, v52, vcc
	v_cndmask_b32_e32 v53, 0, v53, vcc
	v_cndmask_b32_e32 v54, 0, v54, vcc
	v_cndmask_b32_e32 v55, 0, v55, vcc
	v_cndmask_b32_e32 v56, 0, v56, vcc
	v_cndmask_b32_e32 v57, 0, v57, vcc
	v_cndmask_b32_e32 v58, 0, v58, vcc
	v_cndmask_b32_e32 v59, 0, v59, vcc
	v_cndmask_b32_e32 v60, 0, v60, vcc
	v_cndmask_b32_e32 v61, 0, v61, vcc
	v_cndmask_b32_e32 v62, 0, v62, vcc
	v_cndmask_b32_e32 v63, 0, v63, vcc
.Ltp_nz_7:
	ds_write_b32 v23, v48
	ds_write_b32 v23, v49 offset:1040
	ds_write_b32 v23, v50 offset:2080
	ds_write_b32 v23, v51 offset:3120
	ds_write_b32 v23, v52 offset:4160
	ds_write_b32 v23, v53 offset:5200
	ds_write_b32 v23, v54 offset:6240
	ds_write_b32 v23, v55 offset:7280
	ds_write_b32 v23, v56 offset:8320
	ds_write_b32 v23, v57 offset:9360
	ds_write_b32 v23, v58 offset:10400
	ds_write_b32 v23, v59 offset:11440
	ds_write_b32 v23, v60 offset:12480
	ds_write_b32 v23, v61 offset:13520
	ds_write_b32 v23, v62 offset:14560
	ds_write_b32 v23, v63 offset:15600
	v_mov_b32_e32 v3, s81
	v_mad_u32_u24 v2, v112, v3, v113
	s_mov_b64 s[94:95], s[82:83]
	s_cmpk_ge_u32 s40, 0x700
	s_cselect_b32 s0, 1, 0
	s_mul_i32 s1, s0, 0x700
	s_sub_u32 s1, s40, s1
	s_cmpk_ge_u32 s1, 0x4c0
	s_cbranch_scc1 .Ltp_c1_8
	s_movk_i32 s41, 0x50
	s_movk_i32 s42, 0xe8
	s_movk_i32 s43, 0x1210
	s_mov_b32 s44, 4
	s_movk_i32 s45, 0x880
	s_mov_b32 s46, 0x1210000
	s_mov_b32 s47, 0xa18000
	s_branch .Ltp_cj_8

.Ltp_cj_8:
	s_load_dwordx2 s[48:49], s[74:75], s41
	s_load_dwordx2 s[50:51], s[74:75], s42
	s_lshr_b32 s52, s1, s44
	s_lshl_b32 s53, s52, s44
	s_sub_u32 s53, s1, s53
	s_lshl_b32 s52, s52, 6
	s_lshl_b32 s53, s53, 6
	s_sub_i32 s80, s43, s52
	s_mov_b32 s81, s45
	s_mul_i32 s54, s0, s46
	s_mul_i32 s55, s53, s43
	s_lshl_b32 s55, s55, 2
	s_add_u32 s54, s54, s55
	s_mul_i32 s55, s0, s47
	s_mul_i32 s41, s52, s45
	s_add_u32 s55, s55, s41
	s_lshl_b32 s41, s53, 1
	s_add_u32 s55, s55, s41
	s_add_i32 s41, s43, -1
	v_add_u32_e32 v3, s52, v20
	v_min_u32_e32 v3, s41, v3
	s_lshl_b32 s42, s43, 2
	v_mul_u32_u24_e32 v1, s42, v21
	v_lshl_add_u32 v1, v3, 2, v1
	s_lshl_b32 s42, s43, 4
	s_add_i32 s40, s40, s98
	s_waitcnt lgkmcnt(0)
	s_add_u32 s4, s48, s54
	s_addc_u32 s5, s49, 0
	s_add_u32 s82, s50, s55
	s_addc_u32 s83, s51, 0
	s_add_u32 s6, s4, s42
	s_addc_u32 s7, s5, 0
	s_add_u32 s8, s6, s42
	s_addc_u32 s9, s7, 0
	s_add_u32 s10, s8, s42
	s_addc_u32 s11, s9, 0
	s_add_u32 s12, s10, s42
	s_addc_u32 s13, s11, 0
	s_add_u32 s14, s12, s42
	s_addc_u32 s15, s13, 0
	s_add_u32 s16, s14, s42
	s_addc_u32 s17, s15, 0
	s_add_u32 s18, s16, s42
	s_addc_u32 s19, s17, 0
	s_add_u32 s20, s18, s42
	s_addc_u32 s21, s19, 0
	s_add_u32 s22, s20, s42
	s_addc_u32 s23, s21, 0
	s_add_u32 s24, s22, s42
	s_addc_u32 s25, s23, 0
	s_add_u32 s26, s24, s42
	s_addc_u32 s27, s25, 0
	s_add_u32 s28, s26, s42
	s_addc_u32 s29, s27, 0
	s_add_u32 s30, s28, s42
	s_addc_u32 s31, s29, 0
	s_add_u32 s36, s30, s42
	s_addc_u32 s37, s31, 0
	s_add_u32 s38, s36, s42
	s_addc_u32 s39, s37, 0
	s_nop 4
	global_load_dword v48, v1, s[4:5] nt
	global_load_dword v49, v1, s[6:7] nt
	global_load_dword v50, v1, s[8:9] nt
	global_load_dword v51, v1, s[10:11] nt
	global_load_dword v52, v1, s[12:13] nt
	global_load_dword v53, v1, s[14:15] nt
	global_load_dword v54, v1, s[16:17] nt
	global_load_dword v55, v1, s[18:19] nt
	global_load_dword v56, v1, s[20:21] nt
	global_load_dword v57, v1, s[22:23] nt
	global_load_dword v58, v1, s[24:25] nt
	global_load_dword v59, v1, s[26:27] nt
	global_load_dword v60, v1, s[28:29] nt
	global_load_dword v61, v1, s[30:31] nt
	global_load_dword v62, v1, s[36:37] nt
	global_load_dword v63, v1, s[38:39] nt
	s_waitcnt lgkmcnt(0)
	s_barrier
	ds_read2_b32 v[4:5], v28 offset1:65
	ds_read2_b32 v[6:7], v28 offset0:130 offset1:195
	ds_read2_b32 v[8:9], v29 offset0:4 offset1:69
	ds_read2_b32 v[10:11], v29 offset0:134 offset1:199
	ds_read2_b32 v[12:13], v30 offset0:8 offset1:73
	ds_read2_b32 v[14:15], v30 offset0:138 offset1:203
	ds_read2_b32 v[16:17], v31 offset0:12 offset1:77
	ds_read2_b32 v[18:19], v31 offset0:142 offset1:207
	s_waitcnt lgkmcnt(4)
	v_cvt_pk_bf16_f32 v4, v4, v5
	v_cvt_pk_bf16_f32 v5, v6, v7
	v_cvt_pk_bf16_f32 v6, v8, v9
	v_cvt_pk_bf16_f32 v7, v10, v11
	global_store_dwordx4 v2, v[4:7], s[94:95]
	s_waitcnt lgkmcnt(0)
	v_cvt_pk_bf16_f32 v8, v12, v13
	v_cvt_pk_bf16_f32 v9, v14, v15
	v_cvt_pk_bf16_f32 v10, v16, v17
	v_cvt_pk_bf16_f32 v11, v18, v19
	global_store_dwordx4 v2, v[8:11], s[94:95] offset:16
	s_waitcnt vmcnt(52)
	s_cmpk_ge_i32 s84, 0x40
	s_cbranch_scc1 .Ltp_nz_9
	v_cmp_gt_i32_e32 vcc, s84, v20
	v_cndmask_b32_e32 v64, 0, v64, vcc
	v_cndmask_b32_e32 v65, 0, v65, vcc
	v_cndmask_b32_e32 v66, 0, v66, vcc
	v_cndmask_b32_e32 v67, 0, v67, vcc
	v_cndmask_b32_e32 v68, 0, v68, vcc
	v_cndmask_b32_e32 v69, 0, v69, vcc
	v_cndmask_b32_e32 v70, 0, v70, vcc
	v_cndmask_b32_e32 v71, 0, v71, vcc
	v_cndmask_b32_e32 v72, 0, v72, vcc
	v_cndmask_b32_e32 v73, 0, v73, vcc
	v_cndmask_b32_e32 v74, 0, v74, vcc
	v_cndmask_b32_e32 v75, 0, v75, vcc
	v_cndmask_b32_e32 v76, 0, v76, vcc
	v_cndmask_b32_e32 v77, 0, v77, vcc
	v_cndmask_b32_e32 v78, 0, v78, vcc
	v_cndmask_b32_e32 v79, 0, v79, vcc
.Ltp_nz_9:
	ds_write_b32 v22, v64
	ds_write_b32 v22, v65 offset:1040
	ds_write_b32 v22, v66 offset:2080
	ds_write_b32 v22, v67 offset:3120
	ds_write_b32 v22, v68 offset:4160
	ds_write_b32 v22, v69 offset:5200
	ds_write_b32 v22, v70 offset:6240
	ds_write_b32 v22, v71 offset:7280
	ds_write_b32 v22, v72 offset:8320
	ds_write_b32 v22, v73 offset:9360
	ds_write_b32 v22, v74 offset:10400
	ds_write_b32 v22, v75 offset:11440
	ds_write_b32 v22, v76 offset:12480
	ds_write_b32 v22, v77 offset:13520
	ds_write_b32 v22, v78 offset:14560
	ds_write_b32 v22, v79 offset:15600
	v_mov_b32_e32 v3, s85
	v_mad_u32_u24 v2, v112, v3, v113
	s_mov_b64 s[94:95], s[86:87]
	s_cmpk_ge_u32 s40, 0x700
	s_cselect_b32 s0, 1, 0
	s_mul_i32 s1, s0, 0x700
	s_sub_u32 s1, s40, s1
	s_cmpk_ge_u32 s1, 0x4c0
	s_cbranch_scc1 .Ltp_c1_10
	s_movk_i32 s41, 0x50
	s_movk_i32 s42, 0xe8
	s_movk_i32 s43, 0x1210
	s_mov_b32 s44, 4
	s_movk_i32 s45, 0x880
	s_mov_b32 s46, 0x1210000
	s_mov_b32 s47, 0xa18000
	s_branch .Ltp_cj_10

.Ltp_cj_10:
	s_load_dwordx2 s[48:49], s[74:75], s41
	s_load_dwordx2 s[50:51], s[74:75], s42
	s_lshr_b32 s52, s1, s44
	s_lshl_b32 s53, s52, s44
	s_sub_u32 s53, s1, s53
	s_lshl_b32 s52, s52, 6
	s_lshl_b32 s53, s53, 6
	s_sub_i32 s84, s43, s52
	s_mov_b32 s85, s45
	s_mul_i32 s54, s0, s46
	s_mul_i32 s55, s53, s43
	s_lshl_b32 s55, s55, 2
	s_add_u32 s54, s54, s55
	s_mul_i32 s55, s0, s47
	s_mul_i32 s41, s52, s45
	s_add_u32 s55, s55, s41
	s_lshl_b32 s41, s53, 1
	s_add_u32 s55, s55, s41
	s_add_i32 s41, s43, -1
	v_add_u32_e32 v3, s52, v20
	v_min_u32_e32 v3, s41, v3
	s_lshl_b32 s42, s43, 2
	v_mul_u32_u24_e32 v1, s42, v21
	v_lshl_add_u32 v1, v3, 2, v1
	s_lshl_b32 s42, s43, 4
	s_add_i32 s40, s40, s98
	s_waitcnt lgkmcnt(0)
	s_add_u32 s4, s48, s54
	s_addc_u32 s5, s49, 0
	s_add_u32 s86, s50, s55
	s_addc_u32 s87, s51, 0
	s_add_u32 s6, s4, s42
	s_addc_u32 s7, s5, 0
	s_add_u32 s8, s6, s42
	s_addc_u32 s9, s7, 0
	s_add_u32 s10, s8, s42
	s_addc_u32 s11, s9, 0
	s_add_u32 s12, s10, s42
	s_addc_u32 s13, s11, 0
	s_add_u32 s14, s12, s42
	s_addc_u32 s15, s13, 0
	s_add_u32 s16, s14, s42
	s_addc_u32 s17, s15, 0
	s_add_u32 s18, s16, s42
	s_addc_u32 s19, s17, 0
	s_add_u32 s20, s18, s42
	s_addc_u32 s21, s19, 0
	s_add_u32 s22, s20, s42
	s_addc_u32 s23, s21, 0
	s_add_u32 s24, s22, s42
	s_addc_u32 s25, s23, 0
	s_add_u32 s26, s24, s42
	s_addc_u32 s27, s25, 0
	s_add_u32 s28, s26, s42
	s_addc_u32 s29, s27, 0
	s_add_u32 s30, s28, s42
	s_addc_u32 s31, s29, 0
	s_add_u32 s36, s30, s42
	s_addc_u32 s37, s31, 0
	s_add_u32 s38, s36, s42
	s_addc_u32 s39, s37, 0
	s_nop 4
	global_load_dword v64, v1, s[4:5] nt
	global_load_dword v65, v1, s[6:7] nt
	global_load_dword v66, v1, s[8:9] nt
	global_load_dword v67, v1, s[10:11] nt
	global_load_dword v68, v1, s[12:13] nt
	global_load_dword v69, v1, s[14:15] nt
	global_load_dword v70, v1, s[16:17] nt
	global_load_dword v71, v1, s[18:19] nt
	global_load_dword v72, v1, s[20:21] nt
	global_load_dword v73, v1, s[22:23] nt
	global_load_dword v74, v1, s[24:25] nt
	global_load_dword v75, v1, s[26:27] nt
	global_load_dword v76, v1, s[28:29] nt
	global_load_dword v77, v1, s[30:31] nt
	global_load_dword v78, v1, s[36:37] nt
	global_load_dword v79, v1, s[38:39] nt
	s_waitcnt lgkmcnt(0)
	s_barrier
	ds_read2_b32 v[4:5], v24 offset1:65
	ds_read2_b32 v[6:7], v24 offset0:130 offset1:195
	ds_read2_b32 v[8:9], v25 offset0:4 offset1:69
	ds_read2_b32 v[10:11], v25 offset0:134 offset1:199
	ds_read2_b32 v[12:13], v26 offset0:8 offset1:73
	ds_read2_b32 v[14:15], v26 offset0:138 offset1:203
	ds_read2_b32 v[16:17], v27 offset0:12 offset1:77
	ds_read2_b32 v[18:19], v27 offset0:142 offset1:207
	s_waitcnt lgkmcnt(4)
	v_cvt_pk_bf16_f32 v4, v4, v5
	v_cvt_pk_bf16_f32 v5, v6, v7
	v_cvt_pk_bf16_f32 v6, v8, v9
	v_cvt_pk_bf16_f32 v7, v10, v11
	global_store_dwordx4 v2, v[4:7], s[94:95]
	s_waitcnt lgkmcnt(0)
	v_cvt_pk_bf16_f32 v8, v12, v13
	v_cvt_pk_bf16_f32 v9, v14, v15
	v_cvt_pk_bf16_f32 v10, v16, v17
	v_cvt_pk_bf16_f32 v11, v18, v19
	global_store_dwordx4 v2, v[8:11], s[94:95] offset:16
	s_waitcnt vmcnt(54)
	s_cmpk_ge_i32 s88, 0x40
	s_cbranch_scc1 .Ltp_nz_11
	v_cmp_gt_i32_e32 vcc, s88, v20
	v_cndmask_b32_e32 v96, 0, v96, vcc
	v_cndmask_b32_e32 v97, 0, v97, vcc
	v_cndmask_b32_e32 v98, 0, v98, vcc
	v_cndmask_b32_e32 v99, 0, v99, vcc
	v_cndmask_b32_e32 v100, 0, v100, vcc
	v_cndmask_b32_e32 v101, 0, v101, vcc
	v_cndmask_b32_e32 v102, 0, v102, vcc
	v_cndmask_b32_e32 v103, 0, v103, vcc
	v_cndmask_b32_e32 v104, 0, v104, vcc
	v_cndmask_b32_e32 v105, 0, v105, vcc
	v_cndmask_b32_e32 v106, 0, v106, vcc
	v_cndmask_b32_e32 v107, 0, v107, vcc
	v_cndmask_b32_e32 v108, 0, v108, vcc
	v_cndmask_b32_e32 v109, 0, v109, vcc
	v_cndmask_b32_e32 v110, 0, v110, vcc
	v_cndmask_b32_e32 v111, 0, v111, vcc
.Ltp_nz_11:
	ds_write_b32 v23, v96
	ds_write_b32 v23, v97 offset:1040
	ds_write_b32 v23, v98 offset:2080
	ds_write_b32 v23, v99 offset:3120
	ds_write_b32 v23, v100 offset:4160
	ds_write_b32 v23, v101 offset:5200
	ds_write_b32 v23, v102 offset:6240
	ds_write_b32 v23, v103 offset:7280
	ds_write_b32 v23, v104 offset:8320
	ds_write_b32 v23, v105 offset:9360
	ds_write_b32 v23, v106 offset:10400
	ds_write_b32 v23, v107 offset:11440
	ds_write_b32 v23, v108 offset:12480
	ds_write_b32 v23, v109 offset:13520
	ds_write_b32 v23, v110 offset:14560
	ds_write_b32 v23, v111 offset:15600
	v_mov_b32_e32 v3, s89
	v_mad_u32_u24 v2, v112, v3, v113
	s_mov_b64 s[94:95], s[90:91]
	s_cmpk_ge_u32 s40, 0x700
	s_cselect_b32 s0, 1, 0
	s_mul_i32 s1, s0, 0x700
	s_sub_u32 s1, s40, s1
	s_cmpk_ge_u32 s1, 0x4c0
	s_cbranch_scc1 .Ltp_c1_12
	s_movk_i32 s41, 0x50
	s_movk_i32 s42, 0xe8
	s_movk_i32 s43, 0x1210
	s_mov_b32 s44, 4
	s_movk_i32 s45, 0x880
	s_mov_b32 s46, 0x1210000
	s_mov_b32 s47, 0xa18000
	s_branch .Ltp_cj_12

.Ltp_cj_12:
	s_load_dwordx2 s[48:49], s[74:75], s41
	s_load_dwordx2 s[50:51], s[74:75], s42
	s_lshr_b32 s52, s1, s44
	s_lshl_b32 s53, s52, s44
	s_sub_u32 s53, s1, s53
	s_lshl_b32 s52, s52, 6
	s_lshl_b32 s53, s53, 6
	s_sub_i32 s88, s43, s52
	s_mov_b32 s89, s45
	s_mul_i32 s54, s0, s46
	s_mul_i32 s55, s53, s43
	s_lshl_b32 s55, s55, 2
	s_add_u32 s54, s54, s55
	s_mul_i32 s55, s0, s47
	s_mul_i32 s41, s52, s45
	s_add_u32 s55, s55, s41
	s_lshl_b32 s41, s53, 1
	s_add_u32 s55, s55, s41
	s_add_i32 s41, s43, -1
	v_add_u32_e32 v3, s52, v20
	v_min_u32_e32 v3, s41, v3
	s_lshl_b32 s42, s43, 2
	v_mul_u32_u24_e32 v1, s42, v21
	v_lshl_add_u32 v1, v3, 2, v1
	s_lshl_b32 s42, s43, 4
	s_add_i32 s40, s40, s98
	s_waitcnt lgkmcnt(0)
	s_add_u32 s4, s48, s54
	s_addc_u32 s5, s49, 0
	s_add_u32 s90, s50, s55
	s_addc_u32 s91, s51, 0
	s_add_u32 s6, s4, s42
	s_addc_u32 s7, s5, 0
	s_add_u32 s8, s6, s42
	s_addc_u32 s9, s7, 0
	s_add_u32 s10, s8, s42
	s_addc_u32 s11, s9, 0
	s_add_u32 s12, s10, s42
	s_addc_u32 s13, s11, 0
	s_add_u32 s14, s12, s42
	s_addc_u32 s15, s13, 0
	s_add_u32 s16, s14, s42
	s_addc_u32 s17, s15, 0
	s_add_u32 s18, s16, s42
	s_addc_u32 s19, s17, 0
	s_add_u32 s20, s18, s42
	s_addc_u32 s21, s19, 0
	s_add_u32 s22, s20, s42
	s_addc_u32 s23, s21, 0
	s_add_u32 s24, s22, s42
	s_addc_u32 s25, s23, 0
	s_add_u32 s26, s24, s42
	s_addc_u32 s27, s25, 0
	s_add_u32 s28, s26, s42
	s_addc_u32 s29, s27, 0
	s_add_u32 s30, s28, s42
	s_addc_u32 s31, s29, 0
	s_add_u32 s36, s30, s42
	s_addc_u32 s37, s31, 0
	s_add_u32 s38, s36, s42
	s_addc_u32 s39, s37, 0
	s_nop 4
	global_load_dword v96, v1, s[4:5] nt
	global_load_dword v97, v1, s[6:7] nt
	global_load_dword v98, v1, s[8:9] nt
	global_load_dword v99, v1, s[10:11] nt
	global_load_dword v100, v1, s[12:13] nt
	global_load_dword v101, v1, s[14:15] nt
	global_load_dword v102, v1, s[16:17] nt
	global_load_dword v103, v1, s[18:19] nt
	global_load_dword v104, v1, s[20:21] nt
	global_load_dword v105, v1, s[22:23] nt
	global_load_dword v106, v1, s[24:25] nt
	global_load_dword v107, v1, s[26:27] nt
	global_load_dword v108, v1, s[28:29] nt
	global_load_dword v109, v1, s[30:31] nt
	global_load_dword v110, v1, s[36:37] nt
	global_load_dword v111, v1, s[38:39] nt
	s_waitcnt lgkmcnt(0)
	s_barrier
	ds_read2_b32 v[4:5], v28 offset1:65
	ds_read2_b32 v[6:7], v28 offset0:130 offset1:195
	ds_read2_b32 v[8:9], v29 offset0:4 offset1:69
	ds_read2_b32 v[10:11], v29 offset0:134 offset1:199
	ds_read2_b32 v[12:13], v30 offset0:8 offset1:73
	ds_read2_b32 v[14:15], v30 offset0:138 offset1:203
	ds_read2_b32 v[16:17], v31 offset0:12 offset1:77
	ds_read2_b32 v[18:19], v31 offset0:142 offset1:207
	s_waitcnt lgkmcnt(4)
	v_cvt_pk_bf16_f32 v4, v4, v5
	v_cvt_pk_bf16_f32 v5, v6, v7
	v_cvt_pk_bf16_f32 v6, v8, v9
	v_cvt_pk_bf16_f32 v7, v10, v11
	global_store_dwordx4 v2, v[4:7], s[94:95]
	s_waitcnt lgkmcnt(0)
	v_cvt_pk_bf16_f32 v8, v12, v13
	v_cvt_pk_bf16_f32 v9, v14, v15
	v_cvt_pk_bf16_f32 v10, v16, v17
	v_cvt_pk_bf16_f32 v11, v18, v19
	global_store_dwordx4 v2, v[8:11], s[94:95] offset:16
.Ltp_loop:
	s_waitcnt vmcnt(56)
	s_cmpk_ge_i32 s76, 0x40
	s_cbranch_scc1 .Ltp_nz_13
	v_cmp_gt_i32_e32 vcc, s76, v20
	v_cndmask_b32_e32 v32, 0, v32, vcc
	v_cndmask_b32_e32 v33, 0, v33, vcc
	v_cndmask_b32_e32 v34, 0, v34, vcc
	v_cndmask_b32_e32 v35, 0, v35, vcc
	v_cndmask_b32_e32 v36, 0, v36, vcc
	v_cndmask_b32_e32 v37, 0, v37, vcc
	v_cndmask_b32_e32 v38, 0, v38, vcc
	v_cndmask_b32_e32 v39, 0, v39, vcc
	v_cndmask_b32_e32 v40, 0, v40, vcc
	v_cndmask_b32_e32 v41, 0, v41, vcc
	v_cndmask_b32_e32 v42, 0, v42, vcc
	v_cndmask_b32_e32 v43, 0, v43, vcc
	v_cndmask_b32_e32 v44, 0, v44, vcc
	v_cndmask_b32_e32 v45, 0, v45, vcc
	v_cndmask_b32_e32 v46, 0, v46, vcc
	v_cndmask_b32_e32 v47, 0, v47, vcc

.Ltp_cj_14:
	s_load_dwordx2 s[48:49], s[74:75], s41
	s_load_dwordx2 s[50:51], s[74:75], s42
	s_lshr_b32 s52, s1, s44
	s_lshl_b32 s53, s52, s44
	s_sub_u32 s53, s1, s53
	s_lshl_b32 s52, s52, 6
	s_lshl_b32 s53, s53, 6
	s_sub_i32 s76, s43, s52
	s_mov_b32 s77, s45
	s_mul_i32 s54, s0, s46
	s_mul_i32 s55, s53, s43
	s_lshl_b32 s55, s55, 2
	s_add_u32 s54, s54, s55
	s_mul_i32 s55, s0, s47
	s_mul_i32 s41, s52, s45
	s_add_u32 s55, s55, s41
	s_lshl_b32 s41, s53, 1
	s_add_u32 s55, s55, s41
	s_add_i32 s41, s43, -1
	v_add_u32_e32 v3, s52, v20
	v_min_u32_e32 v3, s41, v3
	s_lshl_b32 s42, s43, 2
	v_mul_u32_u24_e32 v1, s42, v21
	v_lshl_add_u32 v1, v3, 2, v1
	s_lshl_b32 s42, s43, 4
	s_add_i32 s40, s40, s98
	s_waitcnt lgkmcnt(0)
	s_add_u32 s4, s48, s54
	s_addc_u32 s5, s49, 0
	s_add_u32 s78, s50, s55
	s_addc_u32 s79, s51, 0
	s_add_u32 s6, s4, s42
	s_addc_u32 s7, s5, 0
	s_add_u32 s8, s6, s42
	s_addc_u32 s9, s7, 0
	s_add_u32 s10, s8, s42
	s_addc_u32 s11, s9, 0
	s_add_u32 s12, s10, s42
	s_addc_u32 s13, s11, 0
	s_add_u32 s14, s12, s42
	s_addc_u32 s15, s13, 0
	s_add_u32 s16, s14, s42
	s_addc_u32 s17, s15, 0
	s_add_u32 s18, s16, s42
	s_addc_u32 s19, s17, 0
	s_add_u32 s20, s18, s42
	s_addc_u32 s21, s19, 0
	s_add_u32 s22, s20, s42
	s_addc_u32 s23, s21, 0
	s_add_u32 s24, s22, s42
	s_addc_u32 s25, s23, 0
	s_add_u32 s26, s24, s42
	s_addc_u32 s27, s25, 0
	s_add_u32 s28, s26, s42
	s_addc_u32 s29, s27, 0
	s_add_u32 s30, s28, s42
	s_addc_u32 s31, s29, 0
	s_add_u32 s36, s30, s42
	s_addc_u32 s37, s31, 0
	s_add_u32 s38, s36, s42
	s_addc_u32 s39, s37, 0
	s_nop 4
	global_load_dword v32, v1, s[4:5] nt
	global_load_dword v33, v1, s[6:7] nt
	global_load_dword v34, v1, s[8:9] nt
	global_load_dword v35, v1, s[10:11] nt
	global_load_dword v36, v1, s[12:13] nt
	global_load_dword v37, v1, s[14:15] nt
	global_load_dword v38, v1, s[16:17] nt
	global_load_dword v39, v1, s[18:19] nt
	global_load_dword v40, v1, s[20:21] nt
	global_load_dword v41, v1, s[22:23] nt
	global_load_dword v42, v1, s[24:25] nt
	global_load_dword v43, v1, s[26:27] nt
	global_load_dword v44, v1, s[28:29] nt
	global_load_dword v45, v1, s[30:31] nt
	global_load_dword v46, v1, s[36:37] nt
	global_load_dword v47, v1, s[38:39] nt
	s_waitcnt lgkmcnt(0)
	s_barrier
	ds_read2_b32 v[4:5], v24 offset1:65
	ds_read2_b32 v[6:7], v24 offset0:130 offset1:195
	ds_read2_b32 v[8:9], v25 offset0:4 offset1:69
	ds_read2_b32 v[10:11], v25 offset0:134 offset1:199
	ds_read2_b32 v[12:13], v26 offset0:8 offset1:73
	ds_read2_b32 v[14:15], v26 offset0:138 offset1:203
	ds_read2_b32 v[16:17], v27 offset0:12 offset1:77
	ds_read2_b32 v[18:19], v27 offset0:142 offset1:207
	s_waitcnt lgkmcnt(4)
	v_cvt_pk_bf16_f32 v4, v4, v5
	v_cvt_pk_bf16_f32 v5, v6, v7
	v_cvt_pk_bf16_f32 v6, v8, v9
	v_cvt_pk_bf16_f32 v7, v10, v11
	global_store_dwordx4 v2, v[4:7], s[94:95]
	s_waitcnt lgkmcnt(0)
	v_cvt_pk_bf16_f32 v8, v12, v13
	v_cvt_pk_bf16_f32 v9, v14, v15
	v_cvt_pk_bf16_f32 v10, v16, v17
	v_cvt_pk_bf16_f32 v11, v18, v19
	global_store_dwordx4 v2, v[8:11], s[94:95] offset:16
	s_waitcnt vmcnt(56)
	s_cmpk_ge_i32 s80, 0x40
	s_cbranch_scc1 .Ltp_nz_15
	v_cmp_gt_i32_e32 vcc, s80, v20
	v_cndmask_b32_e32 v48, 0, v48, vcc
	v_cndmask_b32_e32 v49, 0, v49, vcc
	v_cndmask_b32_e32 v50, 0, v50, vcc
	v_cndmask_b32_e32 v51, 0, v51, vcc
	v_cndmask_b32_e32 v52, 0, v52, vcc
	v_cndmask_b32_e32 v53, 0, v53, vcc
	v_cndmask_b32_e32 v54, 0, v54, vcc
	v_cndmask_b32_e32 v55, 0, v55, vcc
	v_cndmask_b32_e32 v56, 0, v56, vcc
	v_cndmask_b32_e32 v57, 0, v57, vcc
	v_cndmask_b32_e32 v58, 0, v58, vcc
	v_cndmask_b32_e32 v59, 0, v59, vcc
	v_cndmask_b32_e32 v60, 0, v60, vcc
	v_cndmask_b32_e32 v61, 0, v61, vcc
	v_cndmask_b32_e32 v62, 0, v62, vcc
	v_cndmask_b32_e32 v63, 0, v63, vcc

.Ltp_cj_16:
	s_load_dwordx2 s[48:49], s[74:75], s41
	s_load_dwordx2 s[50:51], s[74:75], s42
	s_lshr_b32 s52, s1, s44
	s_lshl_b32 s53, s52, s44
	s_sub_u32 s53, s1, s53
	s_lshl_b32 s52, s52, 6
	s_lshl_b32 s53, s53, 6
	s_sub_i32 s80, s43, s52
	s_mov_b32 s81, s45
	s_mul_i32 s54, s0, s46
	s_mul_i32 s55, s53, s43
	s_lshl_b32 s55, s55, 2
	s_add_u32 s54, s54, s55
	s_mul_i32 s55, s0, s47
	s_mul_i32 s41, s52, s45
	s_add_u32 s55, s55, s41
	s_lshl_b32 s41, s53, 1
	s_add_u32 s55, s55, s41
	s_add_i32 s41, s43, -1
	v_add_u32_e32 v3, s52, v20
	v_min_u32_e32 v3, s41, v3
	s_lshl_b32 s42, s43, 2
	v_mul_u32_u24_e32 v1, s42, v21
	v_lshl_add_u32 v1, v3, 2, v1
	s_lshl_b32 s42, s43, 4
	s_add_i32 s40, s40, s98
	s_waitcnt lgkmcnt(0)
	s_add_u32 s4, s48, s54
	s_addc_u32 s5, s49, 0
	s_add_u32 s82, s50, s55
	s_addc_u32 s83, s51, 0
	s_add_u32 s6, s4, s42
	s_addc_u32 s7, s5, 0
	s_add_u32 s8, s6, s42
	s_addc_u32 s9, s7, 0
	s_add_u32 s10, s8, s42
	s_addc_u32 s11, s9, 0
	s_add_u32 s12, s10, s42
	s_addc_u32 s13, s11, 0
	s_add_u32 s14, s12, s42
	s_addc_u32 s15, s13, 0
	s_add_u32 s16, s14, s42
	s_addc_u32 s17, s15, 0
	s_add_u32 s18, s16, s42
	s_addc_u32 s19, s17, 0
	s_add_u32 s20, s18, s42
	s_addc_u32 s21, s19, 0
	s_add_u32 s22, s20, s42
	s_addc_u32 s23, s21, 0
	s_add_u32 s24, s22, s42
	s_addc_u32 s25, s23, 0
	s_add_u32 s26, s24, s42
	s_addc_u32 s27, s25, 0
	s_add_u32 s28, s26, s42
	s_addc_u32 s29, s27, 0
	s_add_u32 s30, s28, s42
	s_addc_u32 s31, s29, 0
	s_add_u32 s36, s30, s42
	s_addc_u32 s37, s31, 0
	s_add_u32 s38, s36, s42
	s_addc_u32 s39, s37, 0
	s_nop 4
	global_load_dword v48, v1, s[4:5] nt
	global_load_dword v49, v1, s[6:7] nt
	global_load_dword v50, v1, s[8:9] nt
	global_load_dword v51, v1, s[10:11] nt
	global_load_dword v52, v1, s[12:13] nt
	global_load_dword v53, v1, s[14:15] nt
	global_load_dword v54, v1, s[16:17] nt
	global_load_dword v55, v1, s[18:19] nt
	global_load_dword v56, v1, s[20:21] nt
	global_load_dword v57, v1, s[22:23] nt
	global_load_dword v58, v1, s[24:25] nt
	global_load_dword v59, v1, s[26:27] nt
	global_load_dword v60, v1, s[28:29] nt
	global_load_dword v61, v1, s[30:31] nt
	global_load_dword v62, v1, s[36:37] nt
	global_load_dword v63, v1, s[38:39] nt
	s_waitcnt lgkmcnt(0)
	s_barrier
	ds_read2_b32 v[4:5], v28 offset1:65
	ds_read2_b32 v[6:7], v28 offset0:130 offset1:195
	ds_read2_b32 v[8:9], v29 offset0:4 offset1:69
	ds_read2_b32 v[10:11], v29 offset0:134 offset1:199
	ds_read2_b32 v[12:13], v30 offset0:8 offset1:73
	ds_read2_b32 v[14:15], v30 offset0:138 offset1:203
	ds_read2_b32 v[16:17], v31 offset0:12 offset1:77
	ds_read2_b32 v[18:19], v31 offset0:142 offset1:207
	s_waitcnt lgkmcnt(4)
	v_cvt_pk_bf16_f32 v4, v4, v5
	v_cvt_pk_bf16_f32 v5, v6, v7
	v_cvt_pk_bf16_f32 v6, v8, v9
	v_cvt_pk_bf16_f32 v7, v10, v11
	global_store_dwordx4 v2, v[4:7], s[94:95]
	s_waitcnt lgkmcnt(0)
	v_cvt_pk_bf16_f32 v8, v12, v13
	v_cvt_pk_bf16_f32 v9, v14, v15
	v_cvt_pk_bf16_f32 v10, v16, v17
	v_cvt_pk_bf16_f32 v11, v18, v19
	global_store_dwordx4 v2, v[8:11], s[94:95] offset:16
	s_waitcnt vmcnt(56)
	s_cmpk_ge_i32 s84, 0x40
	s_cbranch_scc1 .Ltp_nz_17
	v_cmp_gt_i32_e32 vcc, s84, v20
	v_cndmask_b32_e32 v64, 0, v64, vcc
	v_cndmask_b32_e32 v65, 0, v65, vcc
	v_cndmask_b32_e32 v66, 0, v66, vcc
	v_cndmask_b32_e32 v67, 0, v67, vcc
	v_cndmask_b32_e32 v68, 0, v68, vcc
	v_cndmask_b32_e32 v69, 0, v69, vcc
	v_cndmask_b32_e32 v70, 0, v70, vcc
	v_cndmask_b32_e32 v71, 0, v71, vcc
	v_cndmask_b32_e32 v72, 0, v72, vcc
	v_cndmask_b32_e32 v73, 0, v73, vcc
	v_cndmask_b32_e32 v74, 0, v74, vcc
	v_cndmask_b32_e32 v75, 0, v75, vcc
	v_cndmask_b32_e32 v76, 0, v76, vcc
	v_cndmask_b32_e32 v77, 0, v77, vcc
	v_cndmask_b32_e32 v78, 0, v78, vcc
	v_cndmask_b32_e32 v79, 0, v79, vcc

.Ltp_cj_18:
	s_load_dwordx2 s[48:49], s[74:75], s41
	s_load_dwordx2 s[50:51], s[74:75], s42
	s_lshr_b32 s52, s1, s44
	s_lshl_b32 s53, s52, s44
	s_sub_u32 s53, s1, s53
	s_lshl_b32 s52, s52, 6
	s_lshl_b32 s53, s53, 6
	s_sub_i32 s84, s43, s52
	s_mov_b32 s85, s45
	s_mul_i32 s54, s0, s46
	s_mul_i32 s55, s53, s43
	s_lshl_b32 s55, s55, 2
	s_add_u32 s54, s54, s55
	s_mul_i32 s55, s0, s47
	s_mul_i32 s41, s52, s45
	s_add_u32 s55, s55, s41
	s_lshl_b32 s41, s53, 1
	s_add_u32 s55, s55, s41
	s_add_i32 s41, s43, -1
	v_add_u32_e32 v3, s52, v20
	v_min_u32_e32 v3, s41, v3
	s_lshl_b32 s42, s43, 2
	v_mul_u32_u24_e32 v1, s42, v21
	v_lshl_add_u32 v1, v3, 2, v1
	s_lshl_b32 s42, s43, 4
	s_add_i32 s40, s40, s98
	s_waitcnt lgkmcnt(0)
	s_add_u32 s4, s48, s54
	s_addc_u32 s5, s49, 0
	s_add_u32 s86, s50, s55
	s_addc_u32 s87, s51, 0
	s_add_u32 s6, s4, s42
	s_addc_u32 s7, s5, 0
	s_add_u32 s8, s6, s42
	s_addc_u32 s9, s7, 0
	s_add_u32 s10, s8, s42
	s_addc_u32 s11, s9, 0
	s_add_u32 s12, s10, s42
	s_addc_u32 s13, s11, 0
	s_add_u32 s14, s12, s42
	s_addc_u32 s15, s13, 0
	s_add_u32 s16, s14, s42
	s_addc_u32 s17, s15, 0
	s_add_u32 s18, s16, s42
	s_addc_u32 s19, s17, 0
	s_add_u32 s20, s18, s42
	s_addc_u32 s21, s19, 0
	s_add_u32 s22, s20, s42
	s_addc_u32 s23, s21, 0
	s_add_u32 s24, s22, s42
	s_addc_u32 s25, s23, 0
	s_add_u32 s26, s24, s42
	s_addc_u32 s27, s25, 0
	s_add_u32 s28, s26, s42
	s_addc_u32 s29, s27, 0
	s_add_u32 s30, s28, s42
	s_addc_u32 s31, s29, 0
	s_add_u32 s36, s30, s42
	s_addc_u32 s37, s31, 0
	s_add_u32 s38, s36, s42
	s_addc_u32 s39, s37, 0
	s_nop 4
	global_load_dword v64, v1, s[4:5] nt
	global_load_dword v65, v1, s[6:7] nt
	global_load_dword v66, v1, s[8:9] nt
	global_load_dword v67, v1, s[10:11] nt
	global_load_dword v68, v1, s[12:13] nt
	global_load_dword v69, v1, s[14:15] nt
	global_load_dword v70, v1, s[16:17] nt
	global_load_dword v71, v1, s[18:19] nt
	global_load_dword v72, v1, s[20:21] nt
	global_load_dword v73, v1, s[22:23] nt
	global_load_dword v74, v1, s[24:25] nt
	global_load_dword v75, v1, s[26:27] nt
	global_load_dword v76, v1, s[28:29] nt
	global_load_dword v77, v1, s[30:31] nt
	global_load_dword v78, v1, s[36:37] nt
	global_load_dword v79, v1, s[38:39] nt
	s_waitcnt lgkmcnt(0)
	s_barrier
	ds_read2_b32 v[4:5], v24 offset1:65
	ds_read2_b32 v[6:7], v24 offset0:130 offset1:195
	ds_read2_b32 v[8:9], v25 offset0:4 offset1:69
	ds_read2_b32 v[10:11], v25 offset0:134 offset1:199
	ds_read2_b32 v[12:13], v26 offset0:8 offset1:73
	ds_read2_b32 v[14:15], v26 offset0:138 offset1:203
	ds_read2_b32 v[16:17], v27 offset0:12 offset1:77
	ds_read2_b32 v[18:19], v27 offset0:142 offset1:207
	s_waitcnt lgkmcnt(4)
	v_cvt_pk_bf16_f32 v4, v4, v5
	v_cvt_pk_bf16_f32 v5, v6, v7
	v_cvt_pk_bf16_f32 v6, v8, v9
	v_cvt_pk_bf16_f32 v7, v10, v11
	global_store_dwordx4 v2, v[4:7], s[94:95]
	s_waitcnt lgkmcnt(0)
	v_cvt_pk_bf16_f32 v8, v12, v13
	v_cvt_pk_bf16_f32 v9, v14, v15
	v_cvt_pk_bf16_f32 v10, v16, v17
	v_cvt_pk_bf16_f32 v11, v18, v19
	global_store_dwordx4 v2, v[8:11], s[94:95] offset:16
	s_waitcnt vmcnt(56)
	s_cmpk_ge_i32 s88, 0x40
	s_cbranch_scc1 .Ltp_nz_19
	v_cmp_gt_i32_e32 vcc, s88, v20
	v_cndmask_b32_e32 v96, 0, v96, vcc
	v_cndmask_b32_e32 v97, 0, v97, vcc
	v_cndmask_b32_e32 v98, 0, v98, vcc
	v_cndmask_b32_e32 v99, 0, v99, vcc
	v_cndmask_b32_e32 v100, 0, v100, vcc
	v_cndmask_b32_e32 v101, 0, v101, vcc
	v_cndmask_b32_e32 v102, 0, v102, vcc
	v_cndmask_b32_e32 v103, 0, v103, vcc
	v_cndmask_b32_e32 v104, 0, v104, vcc
	v_cndmask_b32_e32 v105, 0, v105, vcc
	v_cndmask_b32_e32 v106, 0, v106, vcc
	v_cndmask_b32_e32 v107, 0, v107, vcc
	v_cndmask_b32_e32 v108, 0, v108, vcc
	v_cndmask_b32_e32 v109, 0, v109, vcc
	v_cndmask_b32_e32 v110, 0, v110, vcc
	v_cndmask_b32_e32 v111, 0, v111, vcc

.Ltp_cj_20:
	s_load_dwordx2 s[48:49], s[74:75], s41
	s_load_dwordx2 s[50:51], s[74:75], s42
	s_lshr_b32 s52, s1, s44
	s_lshl_b32 s53, s52, s44
	s_sub_u32 s53, s1, s53
	s_lshl_b32 s52, s52, 6
	s_lshl_b32 s53, s53, 6
	s_sub_i32 s88, s43, s52
	s_mov_b32 s89, s45
	s_mul_i32 s54, s0, s46
	s_mul_i32 s55, s53, s43
	s_lshl_b32 s55, s55, 2
	s_add_u32 s54, s54, s55
	s_mul_i32 s55, s0, s47
	s_mul_i32 s41, s52, s45
	s_add_u32 s55, s55, s41
	s_lshl_b32 s41, s53, 1
	s_add_u32 s55, s55, s41
	s_add_i32 s41, s43, -1
	v_add_u32_e32 v3, s52, v20
	v_min_u32_e32 v3, s41, v3
	s_lshl_b32 s42, s43, 2
	v_mul_u32_u24_e32 v1, s42, v21
	v_lshl_add_u32 v1, v3, 2, v1
	s_lshl_b32 s42, s43, 4
	s_add_i32 s40, s40, s98
	s_waitcnt lgkmcnt(0)
	s_add_u32 s4, s48, s54
	s_addc_u32 s5, s49, 0
	s_add_u32 s90, s50, s55
	s_addc_u32 s91, s51, 0
	s_add_u32 s6, s4, s42
	s_addc_u32 s7, s5, 0
	s_add_u32 s8, s6, s42
	s_addc_u32 s9, s7, 0
	s_add_u32 s10, s8, s42
	s_addc_u32 s11, s9, 0
	s_add_u32 s12, s10, s42
	s_addc_u32 s13, s11, 0
	s_add_u32 s14, s12, s42
	s_addc_u32 s15, s13, 0
	s_add_u32 s16, s14, s42
	s_addc_u32 s17, s15, 0
	s_add_u32 s18, s16, s42
	s_addc_u32 s19, s17, 0
	s_add_u32 s20, s18, s42
	s_addc_u32 s21, s19, 0
	s_add_u32 s22, s20, s42
	s_addc_u32 s23, s21, 0
	s_add_u32 s24, s22, s42
	s_addc_u32 s25, s23, 0
	s_add_u32 s26, s24, s42
	s_addc_u32 s27, s25, 0
	s_add_u32 s28, s26, s42
	s_addc_u32 s29, s27, 0
	s_add_u32 s30, s28, s42
	s_addc_u32 s31, s29, 0
	s_add_u32 s36, s30, s42
	s_addc_u32 s37, s31, 0
	s_add_u32 s38, s36, s42
	s_addc_u32 s39, s37, 0
	s_nop 4
	global_load_dword v96, v1, s[4:5] nt
	global_load_dword v97, v1, s[6:7] nt
	global_load_dword v98, v1, s[8:9] nt
	global_load_dword v99, v1, s[10:11] nt
	global_load_dword v100, v1, s[12:13] nt
	global_load_dword v101, v1, s[14:15] nt
	global_load_dword v102, v1, s[16:17] nt
	global_load_dword v103, v1, s[18:19] nt
	global_load_dword v104, v1, s[20:21] nt
	global_load_dword v105, v1, s[22:23] nt
	global_load_dword v106, v1, s[24:25] nt
	global_load_dword v107, v1, s[26:27] nt
	global_load_dword v108, v1, s[28:29] nt
	global_load_dword v109, v1, s[30:31] nt
	global_load_dword v110, v1, s[36:37] nt
	global_load_dword v111, v1, s[38:39] nt
	s_waitcnt lgkmcnt(0)
	s_barrier
	ds_read2_b32 v[4:5], v28 offset1:65
	ds_read2_b32 v[6:7], v28 offset0:130 offset1:195
	ds_read2_b32 v[8:9], v29 offset0:4 offset1:69
	ds_read2_b32 v[10:11], v29 offset0:134 offset1:199
	ds_read2_b32 v[12:13], v30 offset0:8 offset1:73
	ds_read2_b32 v[14:15], v30 offset0:138 offset1:203
	ds_read2_b32 v[16:17], v31 offset0:12 offset1:77
	ds_read2_b32 v[18:19], v31 offset0:142 offset1:207
	s_waitcnt lgkmcnt(4)
	v_cvt_pk_bf16_f32 v4, v4, v5
	v_cvt_pk_bf16_f32 v5, v6, v7
	v_cvt_pk_bf16_f32 v6, v8, v9
	v_cvt_pk_bf16_f32 v7, v10, v11
	global_store_dwordx4 v2, v[4:7], s[94:95]
	s_waitcnt lgkmcnt(0)
	v_cvt_pk_bf16_f32 v8, v12, v13
	v_cvt_pk_bf16_f32 v9, v14, v15
	v_cvt_pk_bf16_f32 v10, v16, v17
	v_cvt_pk_bf16_f32 v11, v18, v19
	global_store_dwordx4 v2, v[8:11], s[94:95] offset:16
	s_add_i32 s73, s73, -1
	s_cmp_lg_u32 s73, 0
	s_cbranch_scc1 .Ltp_loop
	s_waitcnt vmcnt(56)
	s_cmpk_ge_i32 s76, 0x40
	s_cbranch_scc1 .Ltp_nz_21
	v_cmp_gt_i32_e32 vcc, s76, v20
	v_cndmask_b32_e32 v32, 0, v32, vcc
	v_cndmask_b32_e32 v33, 0, v33, vcc
	v_cndmask_b32_e32 v34, 0, v34, vcc
	v_cndmask_b32_e32 v35, 0, v35, vcc
	v_cndmask_b32_e32 v36, 0, v36, vcc
	v_cndmask_b32_e32 v37, 0, v37, vcc
	v_cndmask_b32_e32 v38, 0, v38, vcc
	v_cndmask_b32_e32 v39, 0, v39, vcc
	v_cndmask_b32_e32 v40, 0, v40, vcc
	v_cndmask_b32_e32 v41, 0, v41, vcc
	v_cndmask_b32_e32 v42, 0, v42, vcc
	v_cndmask_b32_e32 v43, 0, v43, vcc
	v_cndmask_b32_e32 v44, 0, v44, vcc
	v_cndmask_b32_e32 v45, 0, v45, vcc
	v_cndmask_b32_e32 v46, 0, v46, vcc
	v_cndmask_b32_e32 v47, 0, v47, vcc
.Ltp_nz_21:
	ds_write_b32 v22, v32
	ds_write_b32 v22, v33 offset:1040
	ds_write_b32 v22, v34 offset:2080
	ds_write_b32 v22, v35 offset:3120
	ds_write_b32 v22, v36 offset:4160
	ds_write_b32 v22, v37 offset:5200
	ds_write_b32 v22, v38 offset:6240
	ds_write_b32 v22, v39 offset:7280
	ds_write_b32 v22, v40 offset:8320
	ds_write_b32 v22, v41 offset:9360
	ds_write_b32 v22, v42 offset:10400
	ds_write_b32 v22, v43 offset:11440
	ds_write_b32 v22, v44 offset:12480
	ds_write_b32 v22, v45 offset:13520
	ds_write_b32 v22, v46 offset:14560
	ds_write_b32 v22, v47 offset:15600
	v_mov_b32_e32 v3, s77
	v_mad_u32_u24 v2, v112, v3, v113
	s_mov_b64 s[94:95], s[78:79]
	s_waitcnt lgkmcnt(0)
	s_barrier
	ds_read2_b32 v[4:5], v24 offset1:65
	ds_read2_b32 v[6:7], v24 offset0:130 offset1:195
	ds_read2_b32 v[8:9], v25 offset0:4 offset1:69
	ds_read2_b32 v[10:11], v25 offset0:134 offset1:199
	ds_read2_b32 v[12:13], v26 offset0:8 offset1:73
	ds_read2_b32 v[14:15], v26 offset0:138 offset1:203
	ds_read2_b32 v[16:17], v27 offset0:12 offset1:77
	ds_read2_b32 v[18:19], v27 offset0:142 offset1:207
	s_waitcnt lgkmcnt(4)
	v_cvt_pk_bf16_f32 v4, v4, v5
	v_cvt_pk_bf16_f32 v5, v6, v7
	v_cvt_pk_bf16_f32 v6, v8, v9
	v_cvt_pk_bf16_f32 v7, v10, v11
	global_store_dwordx4 v2, v[4:7], s[94:95]
	s_waitcnt lgkmcnt(0)
	v_cvt_pk_bf16_f32 v8, v12, v13
	v_cvt_pk_bf16_f32 v9, v14, v15
	v_cvt_pk_bf16_f32 v10, v16, v17
	v_cvt_pk_bf16_f32 v11, v18, v19
	global_store_dwordx4 v2, v[8:11], s[94:95] offset:16
	s_waitcnt vmcnt(40)
	s_cmpk_ge_i32 s80, 0x40
	s_cbranch_scc1 .Ltp_nz_22
	v_cmp_gt_i32_e32 vcc, s80, v20
	v_cndmask_b32_e32 v48, 0, v48, vcc
	v_cndmask_b32_e32 v49, 0, v49, vcc
	v_cndmask_b32_e32 v50, 0, v50, vcc
	v_cndmask_b32_e32 v51, 0, v51, vcc
	v_cndmask_b32_e32 v52, 0, v52, vcc
	v_cndmask_b32_e32 v53, 0, v53, vcc
	v_cndmask_b32_e32 v54, 0, v54, vcc
	v_cndmask_b32_e32 v55, 0, v55, vcc
	v_cndmask_b32_e32 v56, 0, v56, vcc
	v_cndmask_b32_e32 v57, 0, v57, vcc
	v_cndmask_b32_e32 v58, 0, v58, vcc
	v_cndmask_b32_e32 v59, 0, v59, vcc
	v_cndmask_b32_e32 v60, 0, v60, vcc
	v_cndmask_b32_e32 v61, 0, v61, vcc
	v_cndmask_b32_e32 v62, 0, v62, vcc
	v_cndmask_b32_e32 v63, 0, v63, vcc
.Ltp_nz_22:
	ds_write_b32 v23, v48
	ds_write_b32 v23, v49 offset:1040
	ds_write_b32 v23, v50 offset:2080
	ds_write_b32 v23, v51 offset:3120
	ds_write_b32 v23, v52 offset:4160
	ds_write_b32 v23, v53 offset:5200
	ds_write_b32 v23, v54 offset:6240
	ds_write_b32 v23, v55 offset:7280
	ds_write_b32 v23, v56 offset:8320
	ds_write_b32 v23, v57 offset:9360
	ds_write_b32 v23, v58 offset:10400
	ds_write_b32 v23, v59 offset:11440
	ds_write_b32 v23, v60 offset:12480
	ds_write_b32 v23, v61 offset:13520
	ds_write_b32 v23, v62 offset:14560
	ds_write_b32 v23, v63 offset:15600
	v_mov_b32_e32 v3, s81
	v_mad_u32_u24 v2, v112, v3, v113
	s_mov_b64 s[94:95], s[82:83]
	s_waitcnt lgkmcnt(0)
	s_barrier
	ds_read2_b32 v[4:5], v28 offset1:65
	ds_read2_b32 v[6:7], v28 offset0:130 offset1:195
	ds_read2_b32 v[8:9], v29 offset0:4 offset1:69
	ds_read2_b32 v[10:11], v29 offset0:134 offset1:199
	ds_read2_b32 v[12:13], v30 offset0:8 offset1:73
	ds_read2_b32 v[14:15], v30 offset0:138 offset1:203
	ds_read2_b32 v[16:17], v31 offset0:12 offset1:77
	ds_read2_b32 v[18:19], v31 offset0:142 offset1:207
	s_waitcnt lgkmcnt(4)
	v_cvt_pk_bf16_f32 v4, v4, v5
	v_cvt_pk_bf16_f32 v5, v6, v7
	v_cvt_pk_bf16_f32 v6, v8, v9
	v_cvt_pk_bf16_f32 v7, v10, v11
	global_store_dwordx4 v2, v[4:7], s[94:95]
	s_waitcnt lgkmcnt(0)
	v_cvt_pk_bf16_f32 v8, v12, v13
	v_cvt_pk_bf16_f32 v9, v14, v15
	v_cvt_pk_bf16_f32 v10, v16, v17
	v_cvt_pk_bf16_f32 v11, v18, v19
	global_store_dwordx4 v2, v[8:11], s[94:95] offset:16
	s_waitcnt vmcnt(24)
	s_cmpk_ge_i32 s84, 0x40
	s_cbranch_scc1 .Ltp_nz_23
	v_cmp_gt_i32_e32 vcc, s84, v20
	v_cndmask_b32_e32 v64, 0, v64, vcc
	v_cndmask_b32_e32 v65, 0, v65, vcc
	v_cndmask_b32_e32 v66, 0, v66, vcc
	v_cndmask_b32_e32 v67, 0, v67, vcc
	v_cndmask_b32_e32 v68, 0, v68, vcc
	v_cndmask_b32_e32 v69, 0, v69, vcc
	v_cndmask_b32_e32 v70, 0, v70, vcc
	v_cndmask_b32_e32 v71, 0, v71, vcc
	v_cndmask_b32_e32 v72, 0, v72, vcc
	v_cndmask_b32_e32 v73, 0, v73, vcc
	v_cndmask_b32_e32 v74, 0, v74, vcc
	v_cndmask_b32_e32 v75, 0, v75, vcc
	v_cndmask_b32_e32 v76, 0, v76, vcc
	v_cndmask_b32_e32 v77, 0, v77, vcc
	v_cndmask_b32_e32 v78, 0, v78, vcc
	v_cndmask_b32_e32 v79, 0, v79, vcc
.Ltp_nz_23:
	ds_write_b32 v22, v64
	ds_write_b32 v22, v65 offset:1040
	ds_write_b32 v22, v66 offset:2080
	ds_write_b32 v22, v67 offset:3120
	ds_write_b32 v22, v68 offset:4160
	ds_write_b32 v22, v69 offset:5200
	ds_write_b32 v22, v70 offset:6240
	ds_write_b32 v22, v71 offset:7280
	ds_write_b32 v22, v72 offset:8320
	ds_write_b32 v22, v73 offset:9360
	ds_write_b32 v22, v74 offset:10400
	ds_write_b32 v22, v75 offset:11440
	ds_write_b32 v22, v76 offset:12480
	ds_write_b32 v22, v77 offset:13520
	ds_write_b32 v22, v78 offset:14560
	ds_write_b32 v22, v79 offset:15600
	v_mov_b32_e32 v3, s85
	v_mad_u32_u24 v2, v112, v3, v113
	s_mov_b64 s[94:95], s[86:87]
	s_waitcnt lgkmcnt(0)
	s_barrier
	ds_read2_b32 v[4:5], v24 offset1:65
	ds_read2_b32 v[6:7], v24 offset0:130 offset1:195
	ds_read2_b32 v[8:9], v25 offset0:4 offset1:69
	ds_read2_b32 v[10:11], v25 offset0:134 offset1:199
	ds_read2_b32 v[12:13], v26 offset0:8 offset1:73
	ds_read2_b32 v[14:15], v26 offset0:138 offset1:203
	ds_read2_b32 v[16:17], v27 offset0:12 offset1:77
	ds_read2_b32 v[18:19], v27 offset0:142 offset1:207
	s_waitcnt lgkmcnt(4)
	v_cvt_pk_bf16_f32 v4, v4, v5
	v_cvt_pk_bf16_f32 v5, v6, v7
	v_cvt_pk_bf16_f32 v6, v8, v9
	v_cvt_pk_bf16_f32 v7, v10, v11
	global_store_dwordx4 v2, v[4:7], s[94:95]
	s_waitcnt lgkmcnt(0)
	v_cvt_pk_bf16_f32 v8, v12, v13
	v_cvt_pk_bf16_f32 v9, v14, v15
	v_cvt_pk_bf16_f32 v10, v16, v17
	v_cvt_pk_bf16_f32 v11, v18, v19
	global_store_dwordx4 v2, v[8:11], s[94:95] offset:16
	s_waitcnt vmcnt(8)
	s_cmpk_ge_i32 s88, 0x40
	s_cbranch_scc1 .Ltp_nz_24
	v_cmp_gt_i32_e32 vcc, s88, v20
	v_cndmask_b32_e32 v96, 0, v96, vcc
	v_cndmask_b32_e32 v97, 0, v97, vcc
	v_cndmask_b32_e32 v98, 0, v98, vcc
	v_cndmask_b32_e32 v99, 0, v99, vcc
	v_cndmask_b32_e32 v100, 0, v100, vcc
	v_cndmask_b32_e32 v101, 0, v101, vcc
	v_cndmask_b32_e32 v102, 0, v102, vcc
	v_cndmask_b32_e32 v103, 0, v103, vcc
	v_cndmask_b32_e32 v104, 0, v104, vcc
	v_cndmask_b32_e32 v105, 0, v105, vcc
	v_cndmask_b32_e32 v106, 0, v106, vcc
	v_cndmask_b32_e32 v107, 0, v107, vcc
	v_cndmask_b32_e32 v108, 0, v108, vcc
	v_cndmask_b32_e32 v109, 0, v109, vcc
	v_cndmask_b32_e32 v110, 0, v110, vcc
	v_cndmask_b32_e32 v111, 0, v111, vcc
.Ltp_nz_24:
	ds_write_b32 v23, v96
	ds_write_b32 v23, v97 offset:1040
	ds_write_b32 v23, v98 offset:2080
	ds_write_b32 v23, v99 offset:3120
	ds_write_b32 v23, v100 offset:4160
	ds_write_b32 v23, v101 offset:5200
	ds_write_b32 v23, v102 offset:6240
	ds_write_b32 v23, v103 offset:7280
	ds_write_b32 v23, v104 offset:8320
	ds_write_b32 v23, v105 offset:9360
	ds_write_b32 v23, v106 offset:10400
	ds_write_b32 v23, v107 offset:11440
	ds_write_b32 v23, v108 offset:12480
	ds_write_b32 v23, v109 offset:13520
	ds_write_b32 v23, v110 offset:14560
	ds_write_b32 v23, v111 offset:15600
	v_mov_b32_e32 v3, s89
	v_mad_u32_u24 v2, v112, v3, v113
	s_mov_b64 s[94:95], s[90:91]
	s_waitcnt lgkmcnt(0)
	s_barrier
	ds_read2_b32 v[4:5], v28 offset1:65
	ds_read2_b32 v[6:7], v28 offset0:130 offset1:195
	ds_read2_b32 v[8:9], v29 offset0:4 offset1:69
	ds_read2_b32 v[10:11], v29 offset0:134 offset1:199
	ds_read2_b32 v[12:13], v30 offset0:8 offset1:73
	ds_read2_b32 v[14:15], v30 offset0:138 offset1:203
	ds_read2_b32 v[16:17], v31 offset0:12 offset1:77
	ds_read2_b32 v[18:19], v31 offset0:142 offset1:207
	s_waitcnt lgkmcnt(4)
	v_cvt_pk_bf16_f32 v4, v4, v5
	v_cvt_pk_bf16_f32 v5, v6, v7
	v_cvt_pk_bf16_f32 v6, v8, v9
	v_cvt_pk_bf16_f32 v7, v10, v11
	global_store_dwordx4 v2, v[4:7], s[94:95]
	s_waitcnt lgkmcnt(0)
	v_cvt_pk_bf16_f32 v8, v12, v13
	v_cvt_pk_bf16_f32 v9, v14, v15
	v_cvt_pk_bf16_f32 v10, v16, v17
	v_cvt_pk_bf16_f32 v11, v18, v19
	global_store_dwordx4 v2, v[8:11], s[94:95] offset:16
	s_waitcnt lgkmcnt(0)
	s_barrier
